# attention work queue: dynamic tail reordered longest-first (context attention items before retention-output items), on top of mid-stage-barrier GEMM loops
# speedup vs baseline: 1.0043x; 1.0043x over previous
.LBB0_738:
	s_or_b64 exec, exec, s[4:5]
	s_waitcnt lgkmcnt(0)
	s_barrier
	ds_read_b32 v0, v223
	s_mov_b64 s[4:5], -1
	s_waitcnt lgkmcnt(0)
	s_barrier
	v_readfirstlane_b32 s2, v0
	s_cmp_ge_i32 s2, s22
	s_cbranch_scc1 .Lp4_noremap
	s_add_i32 s2, s2, 0xfffffc00
	s_lshl_b32 s14, s21, 1
	s_add_i32 s15, s2, s20
	s_sub_i32 s2, s2, s14
	s_cmp_lt_i32 s2, 0
	s_cselect_b32 s2, s15, s2
	s_add_i32 s2, s2, 0x400
	v_mov_b32_e32 v0, s2
.Lp4_noremap:
.Lp4_have_t:
	v_cmp_le_i32_e32 vcc, s22, v0
	v_readfirstlane_b32 s52, v0
	s_cbranch_vccnz .LBB0_733
	s_cmpk_gt_i32 s52, 0x1ff
	s_cbranch_scc0 .LBB0_794
	s_cmpk_gt_u32 s52, 0x3ff
	s_cbranch_scc0 .LBB0_777
	s_add_i32 s50, s52, 0xfffffc00
	s_cmp_ge_i32 s50, s20
	s_cbranch_scc0 .LBB0_768
	s_sub_i32 s51, s50, s20
	s_cmp_ge_i32 s51, s21
	s_cbranch_scc0 .LBB0_758
	s_sub_i32 s2, s51, s21
	s_lshr_b32 s2, s2, 3
	s_lshl_b32 s53, s52, 7
	s_lshl_b32 s4, s2, 8
	s_and_b32 s5, s53, 0x80
	v_mov_b32_e32 v136, v184
	s_or_b32 s5, s4, s5
	s_addk_i32 s5, 0x4000
	v_ashrrev_i32_e32 v0, 1, v136
	v_readlane_b32 s14, v254, 54
	v_and_b32_e32 v0, 0xffffffe0, v0
	v_and_or_b32 v1, v136, 31, s5
	v_readlane_b32 s15, v254, 55
	v_add_u32_e32 v2, v1, v0
	s_lshl_b32 s5, s52, 6
	v_mov_b64_e32 v[0:1], s[14:15]
	s_addk_i32 s4, 0x4800
	v_mad_i64_i32 v[0:1], s[14:15], v2, s36, v[0:1]
	s_and_b32 s46, s5, 0x180
	s_mov_b32 s5, s3
	s_lshl_b32 s18, s46, 1
	s_lshl_b64 s[14:15], s[4:5], 10
	v_readlane_b32 s4, v253, 13
	v_readlane_b32 s5, v253, 14
	s_add_u32 s4, s4, s14
	v_mov_b32_e32 v10, v184
	s_mov_b32 s19, s3
	s_addc_u32 s5, s5, s15
	global_load_dword v151, v191, s[40:41]
	v_lshl_add_u64 v[138:139], v[0:1], 0, s[18:19]
	v_lshrrev_b32_e32 v11, 1, v10
	s_add_u32 s18, s4, s18
	v_and_b32_e32 v190, 16, v11
	s_addc_u32 s19, s5, 0
	s_lshl_b64 s[4:5], s[2:3], 18
	v_readlane_b32 s2, v255, 2
	v_lshl_add_u64 v[0:1], v[138:139], 0, v[190:191]
	s_add_u32 s2, s2, s4
	v_readlane_b32 s47, v255, 3
	global_load_dwordx4 v[108:111], v[0:1], off
	global_load_dwordx4 v[104:107], v[0:1], off offset:32
	global_load_dwordx4 v[100:103], v[0:1], off offset:64
	global_load_dwordx4 v[96:99], v[0:1], off offset:96
	v_lshlrev_b32_e32 v1, 4, v10
	s_addc_u32 s47, s47, s5
	s_lshl_b32 s46, s46, 9
	v_ashrrev_i32_e32 v2, 1, v10
	v_and_b32_e32 v4, 48, v1
	v_lshlrev_b32_e32 v1, 6, v10
	s_add_u32 s46, s2, s46
	s_movk_i32 s2, 0x90
	v_and_b32_e32 v6, 64, v1
	v_ashrrev_i32_e32 v3, 31, v2
	s_addc_u32 s47, s47, 0
	v_ashrrev_i32_e32 v0, 2, v10
	v_mad_u64_u32 v[142:143], s[48:49], v2, s2, v[6:7]
	v_lshlrev_b64 v[2:3], 9, v[2:3]
	v_lshl_add_u64 v[8:9], s[46:47], 0, v[2:3]
	v_mov_b32_e32 v7, v191
	v_ashrrev_i32_e32 v1, 31, v0
	v_mad_u64_u32 v[140:141], s[48:49], v0, s2, v[4:5]
	v_lshl_add_u64 v[6:7], v[8:9], 0, v[6:7]
	v_lshlrev_b64 v[0:1], 10, v[0:1]
	global_load_dwordx4 v[112:115], v[6:7], off offset:48
	global_load_dwordx4 v[116:119], v[6:7], off offset:32
	global_load_dwordx4 v[120:123], v[6:7], off offset:16
	global_load_dwordx4 v[124:127], v[6:7], off
	v_lshl_add_u64 v[6:7], s[18:19], 0, v[0:1]
	v_mov_b32_e32 v5, v191
	v_lshl_add_u64 v[4:5], v[6:7], 0, v[4:5]
	global_load_dwordx4 v[128:131], v[4:5], off offset:64
	global_load_dwordx4 v[132:135], v[4:5], off
	v_and_b32_e32 v4, 31, v10
	v_mul_u32_u24_e32 v16, 0x90, v4
	v_and_b32_e32 v4, 3, v10
	s_lshl_b32 s48, s52, 15
	v_lshlrev_b32_e32 v6, 1, v10
	v_lshl_add_u64 v[0:1], v[0:1], 0, s[14:15]
	s_and_b32 s2, s53, 0x300
	v_lshlrev_b32_e32 v4, 4, v4
	v_readlane_b32 s60, v252, 4
	s_and_b32 s48, s48, 0x30000
	v_and_b32_e32 v5, 19, v10
	v_and_b32_e32 v6, 8, v6
	v_and_b32_e32 v7, 4, v11
	v_or3_b32 v0, v0, s2, v4
	v_readlane_b32 s74, v252, 18
	v_readlane_b32 s75, v252, 19
	s_or_b32 s4, s4, s48
	v_or3_b32 v5, v5, v6, v7
	v_cmp_lt_i32_e32 vcc, v226, v225
	v_lshl_add_u64 v[144:145], s[74:75], 0, v[0:1]
	v_lshl_add_u64 v[0:1], s[4:5], 0, v[2:3]
	v_and_b32_e32 v2, 1, v10
	v_readlane_b32 s48, v255, 26
	v_cndmask_b32_e32 v6, v224, v226, vcc
	v_mul_u32_u24_e32 v17, 0x90, v5
	v_lshl_or_b32 v0, v2, 6, v0
	v_readlane_b32 s49, v255, 27
	v_mov_b32_e32 v14, v191
	v_mov_b32_e32 v15, v191
	v_lshlrev_b32_e32 v150, 2, v6
	v_lshl_add_u64 v[146:147], s[48:49], 0, v[0:1]
	v_mov_b32_e32 v0, v191
	v_mov_b32_e32 v1, v191
	v_mov_b32_e32 v2, v191
	v_mov_b32_e32 v3, v191
	v_mov_b32_e32 v4, v191
	v_mov_b32_e32 v5, v191
	v_mov_b32_e32 v6, v191
	v_mov_b32_e32 v7, v191
	v_mov_b32_e32 v8, v191
	v_mov_b32_e32 v9, v191
	v_mov_b32_e32 v10, v191
	v_mov_b32_e32 v11, v191
	v_mov_b32_e32 v12, v191
	v_mov_b32_e32 v13, v191
	v_add_u32_e32 v137, v190, v17
	v_add_u32_e32 v148, v190, v16
	v_mov_b64_e32 v[30:31], v[14:15]
	v_mov_b64_e32 v[46:47], v[14:15]
	v_mov_b64_e32 v[62:63], v[14:15]
	v_mov_b32_e32 v143, 0
	v_mov_b32_e32 v149, 0xf149f2ca
	s_mov_b64 s[48:49], 0
	v_mov_b64_e32 v[28:29], v[12:13]
	v_mov_b64_e32 v[26:27], v[10:11]
	v_mov_b64_e32 v[24:25], v[8:9]
	v_mov_b64_e32 v[22:23], v[6:7]
	v_mov_b64_e32 v[20:21], v[4:5]
	v_mov_b64_e32 v[18:19], v[2:3]
	v_mov_b64_e32 v[16:17], v[0:1]
	v_mov_b64_e32 v[44:45], v[12:13]
	v_mov_b64_e32 v[42:43], v[10:11]
	v_mov_b64_e32 v[40:41], v[8:9]
	v_mov_b64_e32 v[38:39], v[6:7]
	v_mov_b64_e32 v[36:37], v[4:5]
	v_mov_b64_e32 v[34:35], v[2:3]
	v_mov_b64_e32 v[32:33], v[0:1]
	v_mov_b64_e32 v[60:61], v[12:13]
	v_mov_b64_e32 v[58:59], v[10:11]
	v_mov_b64_e32 v[56:57], v[8:9]
	v_mov_b64_e32 v[54:55], v[6:7]
	v_mov_b64_e32 v[52:53], v[4:5]
	v_mov_b64_e32 v[50:51], v[2:3]
	v_mov_b64_e32 v[48:49], v[0:1]
	v_readlane_b32 s61, v252, 5
	v_readlane_b32 s62, v252, 6
	v_readlane_b32 s63, v252, 7
	v_readlane_b32 s64, v252, 8
	v_readlane_b32 s65, v252, 9
	v_readlane_b32 s66, v252, 10
	v_readlane_b32 s67, v252, 11
	v_readlane_b32 s68, v252, 12
	v_readlane_b32 s69, v252, 13
	v_readlane_b32 s70, v252, 14
	v_readlane_b32 s71, v252, 15
	v_readlane_b32 s72, v252, 16
	v_readlane_b32 s73, v252, 17
